# v12: merge-branch K-loop re-scheduled with immediate-offset fragment reads, 3-buffer A ring, SALU m0 (fewer VALU per MFMA)
# speedup vs baseline: 1.0414x; 1.0041x over previous
.LBB0_78:
.LBB0_79:
	v_readfirstlane_b32 s7, v235
	s_mul_i32 s67, s49, 0xc000
	s_add_i32 s8, s49, -1
	s_cmp_eq_u32 s49, 0
	s_cselect_b32 s8, 2, s8
	s_mul_i32 s8, s8, 0xc000
	s_add_i32 s6, s8, s7
	v_add3_u32 v239, s67, v238, v237
	v_add3_u32 v244, s67, v236, v237
	ds_read_b128 v[130:133], v244 offset:32768
	ds_read_b128 v[134:137], v244 offset:34816
	ds_read_b128 v[146:149], v239 offset:0
	ds_read_b128 v[246:249], v239 offset:2048
	ds_read_b128 v[240:243], v239 offset:4096
.Lgb_loop:
	s_waitcnt lgkmcnt(2)
	v_mfma_f32_16x16x32_bf16 v[126:129], v[146:149], v[130:133], v[126:129]
	v_mfma_f32_16x16x32_bf16 v[122:125], v[146:149], v[134:137], v[122:125]
	ds_read_b128 v[146:149], v239 offset:6144
	s_cmp_gt_u32 s48, 5
	s_cbranch_scc1 .Lgb_nodma0
	v_lshl_add_u64 v[250:251], v[224:225], 0, s[44:45]
	s_add_i32 m0, s6, 0x0
	s_nop 0
	global_load_lds_dwordx4 v[250:251], off
.Lgb_nodma0:
	s_waitcnt lgkmcnt(2)
	v_mfma_f32_16x16x32_bf16 v[118:121], v[246:249], v[130:133], v[118:121]
	v_mfma_f32_16x16x32_bf16 v[114:117], v[246:249], v[134:137], v[114:117]
	ds_read_b128 v[246:249], v239 offset:8192
	s_cmp_gt_u32 s48, 5
	s_cbranch_scc1 .Lgb_nodma1
	v_lshl_add_u64 v[250:251], v[222:223], 0, s[44:45]
	s_add_i32 m0, s6, 0x8000
	s_nop 0
	global_load_lds_dwordx4 v[250:251], off
.Lgb_nodma1:
	s_waitcnt lgkmcnt(2)
	v_mfma_f32_16x16x32_bf16 v[110:113], v[240:243], v[130:133], v[110:113]
	v_mfma_f32_16x16x32_bf16 v[106:109], v[240:243], v[134:137], v[106:109]
	ds_read_b128 v[240:243], v239 offset:10240
	s_cmp_gt_u32 s48, 5
	s_cbranch_scc1 .Lgb_nodma2
	v_lshl_add_u64 v[250:251], v[220:221], 0, s[44:45]
	s_add_i32 m0, s6, 0x2000
	s_nop 0
	global_load_lds_dwordx4 v[250:251], off
.Lgb_nodma2:
	s_waitcnt lgkmcnt(2)
	v_mfma_f32_16x16x32_bf16 v[102:105], v[146:149], v[130:133], v[102:105]
	v_mfma_f32_16x16x32_bf16 v[98:101], v[146:149], v[134:137], v[98:101]
	ds_read_b128 v[146:149], v239 offset:12288
	s_cmp_gt_u32 s48, 5
	s_cbranch_scc1 .Lgb_nodma3
	v_lshl_add_u64 v[250:251], v[218:219], 0, s[44:45]
	s_add_i32 m0, s6, 0xa000
	s_nop 0
	global_load_lds_dwordx4 v[250:251], off
.Lgb_nodma3:
	s_waitcnt lgkmcnt(2)
	v_mfma_f32_16x16x32_bf16 v[94:97], v[246:249], v[130:133], v[94:97]
	v_mfma_f32_16x16x32_bf16 v[90:93], v[246:249], v[134:137], v[90:93]
	ds_read_b128 v[246:249], v239 offset:14336
	ds_read_b128 v[138:141], v244 offset:33792
	s_cmp_gt_u32 s48, 5
	s_cbranch_scc1 .Lgb_nodma4
	v_lshl_add_u64 v[250:251], v[216:217], 0, s[44:45]
	s_add_i32 m0, s6, 0x4000
	s_nop 0
	global_load_lds_dwordx4 v[250:251], off
.Lgb_nodma4:
	s_waitcnt lgkmcnt(3)
	v_mfma_f32_16x16x32_bf16 v[86:89], v[240:243], v[130:133], v[86:89]
	v_mfma_f32_16x16x32_bf16 v[82:85], v[240:243], v[134:137], v[82:85]
	ds_read_b128 v[240:243], v239 offset:1024
	ds_read_b128 v[142:145], v244 offset:35840
	s_cmp_gt_u32 s48, 5
	s_cbranch_scc1 .Lgb_nodma5
	v_lshl_add_u64 v[250:251], v[214:215], 0, s[44:45]
	s_add_i32 m0, s6, 0x6000
	s_nop 0
	global_load_lds_dwordx4 v[250:251], off
.Lgb_nodma5:
	s_waitcnt lgkmcnt(4)
	v_mfma_f32_16x16x32_bf16 v[78:81], v[146:149], v[130:133], v[78:81]
	v_mfma_f32_16x16x32_bf16 v[74:77], v[146:149], v[134:137], v[74:77]
	ds_read_b128 v[146:149], v239 offset:3072
	s_waitcnt lgkmcnt(4)
	v_mfma_f32_16x16x32_bf16 v[66:69], v[246:249], v[130:133], v[66:69]
	v_mfma_f32_16x16x32_bf16 v[54:57], v[246:249], v[134:137], v[54:57]
	ds_read_b128 v[246:249], v239 offset:5120
	s_waitcnt lgkmcnt(3)
	v_mfma_f32_16x16x32_bf16 v[126:129], v[240:243], v[138:141], v[126:129]
	s_waitcnt lgkmcnt(2)
	v_mfma_f32_16x16x32_bf16 v[122:125], v[240:243], v[142:145], v[122:125]
	ds_read_b128 v[240:243], v239 offset:7168
	s_waitcnt lgkmcnt(2)
	v_mfma_f32_16x16x32_bf16 v[118:121], v[146:149], v[138:141], v[118:121]
	v_mfma_f32_16x16x32_bf16 v[114:117], v[146:149], v[142:145], v[114:117]
	ds_read_b128 v[146:149], v239 offset:9216
	s_waitcnt lgkmcnt(2)
	v_mfma_f32_16x16x32_bf16 v[110:113], v[246:249], v[138:141], v[110:113]
	v_mfma_f32_16x16x32_bf16 v[106:109], v[246:249], v[142:145], v[106:109]
	ds_read_b128 v[246:249], v239 offset:11264
	s_waitcnt lgkmcnt(2)
	v_mfma_f32_16x16x32_bf16 v[102:105], v[240:243], v[138:141], v[102:105]
	v_mfma_f32_16x16x32_bf16 v[98:101], v[240:243], v[142:145], v[98:101]
	ds_read_b128 v[240:243], v239 offset:13312
	s_waitcnt lgkmcnt(2)
	v_mfma_f32_16x16x32_bf16 v[94:97], v[146:149], v[138:141], v[94:97]
	v_mfma_f32_16x16x32_bf16 v[90:93], v[146:149], v[142:145], v[90:93]
	s_waitcnt lgkmcnt(1)
	v_mfma_f32_16x16x32_bf16 v[86:89], v[246:249], v[138:141], v[86:89]
	v_mfma_f32_16x16x32_bf16 v[82:85], v[246:249], v[142:145], v[82:85]
	s_waitcnt lgkmcnt(0)
	v_mfma_f32_16x16x32_bf16 v[78:81], v[240:243], v[138:141], v[78:81]
	v_mfma_f32_16x16x32_bf16 v[74:77], v[240:243], v[142:145], v[74:77]
	ds_read_b128 v[240:243], v239 offset:15360
	s_waitcnt lgkmcnt(0)
	s_cmp_gt_u32 s48, 5
	s_cbranch_scc1 .Lgb_w0
	s_waitcnt vmcnt(6)
	s_branch .Lgb_wd

.Lgb_wd:
	s_barrier
	s_add_i32 s48, s48, 1
	s_add_u32 s44, s44, 0x80
	s_addc_u32 s45, s45, 0
	s_add_i32 s9, s49, 1
	s_cmp_lg_u32 s49, 2
	s_cselect_b32 s49, s9, 0
	s_cmpk_eq_i32 s44, 0x400
	s_cbranch_scc1 .Lgb_tail
	s_mul_i32 s67, s49, 0xc000
	s_add_i32 s8, s49, -1
	s_cmp_eq_u32 s49, 0
	s_cselect_b32 s8, 2, s8
	s_mul_i32 s8, s8, 0xc000
	s_add_i32 s6, s8, s7
	v_add3_u32 v239, s67, v238, v237
	v_add3_u32 v244, s67, v236, v237
	ds_read_b128 v[130:133], v244 offset:32768
	ds_read_b128 v[134:137], v244 offset:34816
	ds_read_b128 v[146:149], v239 offset:0
	ds_read_b128 v[246:249], v239 offset:2048
	v_mfma_f32_16x16x32_bf16 v[66:69], v[240:243], v[138:141], v[66:69]
	v_mfma_f32_16x16x32_bf16 v[54:57], v[240:243], v[142:145], v[54:57]
	ds_read_b128 v[240:243], v239 offset:4096
	s_branch .Lgb_loop
.Lgb_tail:
	v_mfma_f32_16x16x32_bf16 v[66:69], v[240:243], v[138:141], v[66:69]
	v_mfma_f32_16x16x32_bf16 v[54:57], v[240:243], v[142:145], v[54:57]
